# prompt-tile top-k: local argmax as two interleaved chains and batched clear compares (compare to select wait states filled instead of s_nop)
# baseline (speedup 1.0000x reference)
.LBB0_1403:
	v_max_f32_e32 v36, v93, v93
	v_cmp_lt_f32_e32 vcc, -2.0, v93
	v_max_f32_e32 v36, -2.0, v36
	v_mov_b32_e32 v42, 0
	v_max_f32_e32 v37, v56, v56
	v_cndmask_b32_e32 v35, v174, v92, vcc
	v_mov_b32_e32 v252, v54
	v_cmp_gt_f32_e32 vcc, v95, v36
	v_cmp_gt_f32_e64 s[8:9], v57, v37
	v_max_f32_e32 v36, v36, v95
	v_max_f32_e32 v37, v37, v57
	v_cndmask_b32_e32 v35, v35, v94, vcc
	v_cndmask_b32_e64 v252, v252, v55, s[8:9]
	v_cmp_gt_f32_e32 vcc, v64, v36
	v_cmp_gt_f32_e64 s[8:9], v48, v37
	v_max_f32_e32 v36, v36, v64
	v_max_f32_e32 v37, v37, v48
	v_cndmask_b32_e32 v35, v35, v62, vcc
	v_cndmask_b32_e64 v252, v252, v46, s[8:9]
	v_cmp_gt_f32_e32 vcc, v63, v36
	v_cmp_gt_f32_e64 s[8:9], v49, v37
	v_max_f32_e32 v36, v36, v63
	v_max_f32_e32 v37, v37, v49
	v_cndmask_b32_e32 v35, v35, v1, vcc
	v_cndmask_b32_e64 v252, v252, v47, s[8:9]
	v_cmp_gt_f32_e32 vcc, v76, v36
	v_cmp_gt_f32_e64 s[8:9], v40, v37
	v_max_f32_e32 v36, v36, v76
	v_max_f32_e32 v37, v37, v40
	v_cndmask_b32_e32 v35, v35, v66, vcc
	v_cndmask_b32_e64 v252, v252, v38, s[8:9]
	v_cmp_gt_f32_e32 vcc, v67, v36
	v_cmp_gt_f32_e64 s[8:9], v41, v37
	v_max_f32_e32 v36, v36, v67
	v_max_f32_e32 v37, v37, v41
	v_cndmask_b32_e32 v35, v35, v65, vcc
	v_cndmask_b32_e64 v252, v252, v39, s[8:9]
	v_cmp_gt_f32_e32 vcc, v70, v36
	v_cmp_gt_f32_e64 s[8:9], v32, v37
	v_max_f32_e32 v36, v36, v70
	v_max_f32_e32 v37, v37, v32
	v_cndmask_b32_e32 v35, v35, v68, vcc
	v_cndmask_b32_e64 v252, v252, v30, s[8:9]
	v_cmp_gt_f32_e32 vcc, v71, v36
	v_cmp_gt_f32_e64 s[8:9], v33, v37
	v_max_f32_e32 v36, v36, v71
	v_max_f32_e32 v37, v37, v33
	v_cndmask_b32_e32 v35, v35, v69, vcc
	v_cndmask_b32_e64 v252, v252, v31, s[8:9]
	v_cmp_gt_f32_e32 vcc, v37, v36
	v_max_f32_e32 v253, v36, v37
	s_nop 0
	v_cndmask_b32_e32 v36, v35, v252, vcc
	v_mov_b32_e32 v35, v253
	v_mov_b32_e32 v37, 0
	v_mov_b32_dpp v42, v36 row_ror:8 row_mask:0xf bank_mask:0xf
	s_nop 0
	v_mov_b32_dpp v37, v35 row_ror:8 row_mask:0xf bank_mask:0xf
	v_cmp_lt_f32_e64 s[12:13], v35, v37
	v_cmp_nlt_f32_e32 vcc, v35, v37
	s_and_saveexec_b64 s[14:15], vcc
	v_cmp_eq_f32_e32 vcc, v35, v37
	v_cmp_lt_i32_e64 s[8:9], v42, v36
	s_and_b64 s[8:9], vcc, s[8:9]
	s_andn2_b64 s[12:13], s[12:13], exec
	s_and_b64 s[8:9], s[8:9], exec
	s_or_b64 s[12:13], s[12:13], s[8:9]
	s_or_b64 exec, exec, s[14:15]
	s_and_saveexec_b64 s[8:9], s[12:13]
	v_mov_b32_e32 v35, v37
	v_mov_b32_e32 v36, v42
	s_or_b64 exec, exec, s[8:9]
	v_mov_b32_e32 v37, v35
	s_nop 1
	v_permlane16_swap_b32_e32 v35, v37
	v_mov_b32_e32 v42, v36
	s_nop 1
	v_permlane16_swap_b32_e32 v36, v42
	v_cmp_ngt_f32_e32 vcc, v37, v35
	s_mov_b64 s[14:15], -1
	s_mov_b64 s[8:9], -1
	s_and_saveexec_b64 s[12:13], vcc
	v_cmp_eq_f32_e32 vcc, v37, v35
	v_cmp_lt_i32_e64 s[8:9], v42, v36
	s_and_b64 s[8:9], vcc, s[8:9]
	s_orn2_b64 s[8:9], s[8:9], exec
	s_or_b64 exec, exec, s[12:13]
	v_cndmask_b32_e64 v37, v35, v37, s[8:9]
	v_cndmask_b32_e64 v36, v36, v42, s[8:9]
	v_mov_b32_e32 v42, v37
	s_nop 1
	v_permlane32_swap_b32_e32 v37, v42
	v_mov_b32_e32 v35, v36
	s_nop 1
	v_permlane32_swap_b32_e32 v36, v35
	v_cmp_ngt_f32_e32 vcc, v42, v37
	s_and_saveexec_b64 s[12:13], vcc
	v_cmp_eq_f32_e32 vcc, v42, v37
	v_cmp_lt_i32_e64 s[8:9], v35, v36
	s_and_b64 s[8:9], vcc, s[8:9]
	s_orn2_b64 s[14:15], s[8:9], exec
	s_or_b64 exec, exec, s[12:13]
	v_cndmask_b32_e64 v37, v37, v42, s[14:15]
	v_cmp_le_f32_e32 vcc, 0, v37
	s_cmp_eq_u64 vcc, 0
	s_cselect_b64 s[12:13], -1, 0
	s_cbranch_vccz .LBB0_1415
	v_cmp_lt_u32_e64 s[8:9], s7, v34
	v_cndmask_b32_e64 v35, v36, v35, s[14:15]
	s_and_b64 s[14:15], s[8:9], vcc
	s_and_saveexec_b64 s[8:9], s[14:15]
	s_cbranch_execz .LBB0_1414
	v_bfe_u32 v37, v35, 5, 2
	v_lshlrev_b32_e64 v36, v35, 1
	v_cmp_eq_u32_e32 vcc, 0, v37
	s_nop 1
	v_cndmask_b32_e32 v42, 0, v36, vcc
	v_cmp_eq_u32_e32 vcc, 1, v37
	v_or_b32_e32 v26, v42, v26
	s_nop 0
	v_cndmask_b32_e32 v42, 0, v36, vcc
	v_cmp_eq_u32_e32 vcc, 2, v37
	v_or_b32_e32 v27, v42, v27
	s_nop 0
	v_cndmask_b32_e32 v42, 0, v36, vcc
	v_cmp_eq_u32_e32 vcc, 3, v37
	v_or_b32_e32 v28, v42, v28
	s_nop 0
	v_cndmask_b32_e32 v36, 0, v36, vcc
	v_or_b32_e32 v29, v36, v29
.LBB0_1414:
	s_or_b64 exec, exec, s[8:9]
	v_cmp_ne_u32_e64 s[8:9], v92, v35
	v_cmp_ne_u32_e64 s[14:15], v94, v35
	v_cmp_ne_u32_e64 s[98:99], v1, v35
	v_cmp_ne_u32_e32 vcc, v62, v35
	v_cndmask_b32_e64 v93, -2.0, v93, s[8:9]
	v_cndmask_b32_e64 v95, -2.0, v95, s[14:15]
	v_cndmask_b32_e64 v63, -2.0, v63, s[98:99]
	v_cndmask_b32_e32 v64, -2.0, v64, vcc
	v_cmp_ne_u32_e64 s[8:9], v65, v35
	v_cmp_ne_u32_e64 s[14:15], v66, v35
	v_cmp_ne_u32_e64 s[98:99], v69, v35
	v_cmp_ne_u32_e32 vcc, v68, v35
	v_cndmask_b32_e64 v67, -2.0, v67, s[8:9]
	v_cndmask_b32_e64 v76, -2.0, v76, s[14:15]
	v_cndmask_b32_e64 v71, -2.0, v71, s[98:99]
	v_cndmask_b32_e32 v70, -2.0, v70, vcc
	v_cmp_ne_u32_e64 s[8:9], v55, v35
	v_cmp_ne_u32_e64 s[14:15], v54, v35
	v_cmp_ne_u32_e64 s[98:99], v47, v35
	v_cmp_ne_u32_e32 vcc, v46, v35
	v_cndmask_b32_e64 v57, -2.0, v57, s[8:9]
	v_cndmask_b32_e64 v56, -2.0, v56, s[14:15]
	v_cndmask_b32_e64 v49, -2.0, v49, s[98:99]
	v_cndmask_b32_e32 v48, -2.0, v48, vcc
	v_cmp_ne_u32_e64 s[8:9], v39, v35
	v_cmp_ne_u32_e64 s[14:15], v38, v35
	v_cmp_ne_u32_e64 s[98:99], v31, v35
	v_cmp_ne_u32_e32 vcc, v30, v35
	v_cndmask_b32_e64 v41, -2.0, v41, s[8:9]
	v_cndmask_b32_e64 v40, -2.0, v40, s[14:15]
	v_cndmask_b32_e64 v33, -2.0, v33, s[98:99]
	v_cndmask_b32_e32 v32, -2.0, v32, vcc

	.amdhsa_kernel _Z6mk_fwd4Args
		.amdhsa_group_segment_fixed_size 0
		.amdhsa_private_segment_fixed_size 0
		.amdhsa_kernarg_size 536
		.amdhsa_user_sgpr_count 2
		.amdhsa_user_sgpr_dispatch_ptr 0
		.amdhsa_user_sgpr_queue_ptr 0
		.amdhsa_user_sgpr_kernarg_segment_ptr 1
		.amdhsa_user_sgpr_dispatch_id 0
		.amdhsa_user_sgpr_kernarg_preload_length 0
		.amdhsa_user_sgpr_kernarg_preload_offset 0
		.amdhsa_user_sgpr_private_segment_size 0
		.amdhsa_uses_dynamic_stack 0
		.amdhsa_enable_private_segment 0
		.amdhsa_system_sgpr_workgroup_id_x 1
		.amdhsa_system_sgpr_workgroup_id_y 0
		.amdhsa_system_sgpr_workgroup_id_z 0
		.amdhsa_system_sgpr_workgroup_info 0
		.amdhsa_system_vgpr_workitem_id 0
		.amdhsa_next_free_vgpr 256
		.amdhsa_next_free_sgpr 100
		.amdhsa_accum_offset 256
		.amdhsa_reserve_vcc 1
		.amdhsa_float_round_mode_32 0
		.amdhsa_float_round_mode_16_64 0
		.amdhsa_float_denorm_mode_32 3
		.amdhsa_float_denorm_mode_16_64 3
		.amdhsa_dx10_clamp 1
		.amdhsa_ieee_mode 1
		.amdhsa_fp16_overflow 0
		.amdhsa_tg_split 0
		.amdhsa_exception_fp_ieee_invalid_op 0
		.amdhsa_exception_fp_denorm_src 0
		.amdhsa_exception_fp_ieee_div_zero 0
		.amdhsa_exception_fp_ieee_overflow 0
		.amdhsa_exception_fp_ieee_underflow 0
		.amdhsa_exception_fp_ieee_inexact 0
		.amdhsa_exception_int_div_zero 0
	.end_amdhsa_kernel

amdhsa.kernels:
  - .agpr_count:     0
    .args:
      - .offset:         0
        .size:           280
        .value_kind:     by_value
      - .offset:         280
        .size:           4
        .value_kind:     hidden_block_count_x
      - .offset:         284
        .size:           4
        .value_kind:     hidden_block_count_y
      - .offset:         288
        .size:           4
        .value_kind:     hidden_block_count_z
      - .offset:         292
        .size:           2
        .value_kind:     hidden_group_size_x
      - .offset:         294
        .size:           2
        .value_kind:     hidden_group_size_y
      - .offset:         296
        .size:           2
        .value_kind:     hidden_group_size_z
      - .offset:         298
        .size:           2
        .value_kind:     hidden_remainder_x
      - .offset:         300
        .size:           2
        .value_kind:     hidden_remainder_y
      - .offset:         302
        .size:           2
        .value_kind:     hidden_remainder_z
      - .offset:         320
        .size:           8
        .value_kind:     hidden_global_offset_x
      - .offset:         328
        .size:           8
        .value_kind:     hidden_global_offset_y
      - .offset:         336
        .size:           8
        .value_kind:     hidden_global_offset_z
      - .offset:         344
        .size:           2
        .value_kind:     hidden_grid_dims
      - .offset:         400
        .size:           4
        .value_kind:     hidden_dynamic_lds_size
    .group_segment_fixed_size: 0
    .kernarg_segment_align: 8
    .kernarg_segment_size: 536
    .language:       OpenCL C
    .language_version:
      - 2
      - 0
    .max_flat_workgroup_size: 512
    .name:           _Z6mk_fwd4Args
    .private_segment_fixed_size: 0
    .sgpr_count:     106
    .sgpr_spill_count: 115
    .symbol:         _Z6mk_fwd4Args.kd
    .uniform_work_group_size: 1
    .uses_dynamic_stack: false
    .vgpr_count:     256
    .vgpr_spill_count: 0
    .wavefront_size: 64
